# scan S-update re-scheduled with two k^T accumulators in flight; attention row-sum as add tree
# speedup vs baseline: 1.1780x; 1.0246x over previous
; __device__ __forceinline__ void scan_chunked(const Params& p, unsigned char* smem, int bh, f32x16 (&S)[4], const int c_begin, const int c_end) {
;     ...
;     {
;       const u16* Xq = DX + ((size_t)(bh * NCH + c) * 3) * 8192; const u16* Xk = Xq + 8192; const u16* Xv = Xk + 8192;
;       const u16* Tg = TA + (size_t)(bh * NCH + c) * 8704; const u16* Ag = Tg + 4096;
; #pragma unroll
;       for (int i = 0; i < 4; ++i) { pk[i] = *(const u32x4*)(Xk + (tid + 256 * i) * 8); pq[i] = *(const u32x4*)(Xq + (tid + 256 * i) * 8); }
; #pragma unroll
;       for (int i = 0; i < 2; ++i) { pT[i] = *(const u32x4*)(Tg + (tid + 256 * i) * 8); pA[i] = *(const u32x4*)(Ag + (tid + 256 * i) * 8); }
;       psc = ((const float*)(Tg + 8192))[tid];
; #pragma unroll
;       for (int i = 0; i < 8; ++i) pv[i] = *(const uint2*)(Xv + (wave * 32 + l31) * 64 + 32 * (i >> 2) + 8 * (i & 3) + 4 * hf);
;     }
; #pragma unroll
;     for (int i = 0; i < 4; ++i) {
;       int idx = tid + 256 * i; int row = idx >> 4, ch = idx & 15; const int po = (ch >> 1) * 16 + (ch & 1) * 4;
;       u16* dk = sk + row * 136 + po; *(uint2*)dk = make_uint2(pk[i].x, pk[i].y); *(uint2*)(dk + 8) = make_uint2(pk[i].z, pk[i].w);
;       u16* dq = sq + row * 136 + po; *(uint2*)dq = make_uint2(pq[i].x, pq[i].y); *(uint2*)(dq + 8) = make_uint2(pq[i].z, pq[i].w);
;     }
; #pragma unroll
;     for (int i = 0; i < 2; ++i) {
;       int idx = tid + 256 * i; int row = idx >> 3, ch = idx & 7; const int po = (ch >> 1) * 16 + (ch & 1) * 4;
;       u16* dt = sT + row * 72 + po; *(uint2*)dt = make_uint2(pT[i].x, pT[i].y); *(uint2*)(dt + 8) = make_uint2(pT[i].z, pT[i].w);
;       u16* da = sA + row * 72 + po; *(uint2*)da = make_uint2(pA[i].x, pA[i].y); *(uint2*)(da + 8) = make_uint2(pA[i].z, pA[i].w);
;     }
;     sSC[tid] = psc;
;     lds_barrier();
;     __builtin_amdgcn_sched_barrier(0);
;     u32x4 yf[4];
;     {
;       f32x16 x0, x1;
; #pragma unroll
;       for (int r = 0; r < 16; ++r) { x0[r] = 0.f; x1[r] = 0.f; }
; #pragma unroll
;       for (int dt = 0; dt < 4; ++dt)
; #pragma unroll
;         for (int s = 0; s < 2; ++s) {
;           u32x4 sb = {cvtpk(S[dt][8 * s + 0], S[dt][8 * s + 1]), cvtpk(S[dt][8 * s + 2], S[dt][8 * s + 3]), cvtpk(S[dt][8 * s + 4], S[dt][8 * s + 5]), cvtpk(S[dt][8 * s + 6], S[dt][8 * s + 7])};
;           const bf16x8 k0f = *(const bf16x8*)(sk + (l31) * 136 + 32 * dt + 16 * s + 8 * hf);
.LBB0_315:
	s_add_i32 s21, s7, s19
	s_mul_i32 s12, s21, 0xc000
	s_mul_hi_u32 s13, s21, 0xc000
	s_add_u32 s12, s2, s12
	s_addc_u32 s13, s16, s13
	s_add_u32 s14, s12, 0x4000
	s_addc_u32 s15, s13, 0
	s_mul_hi_u32 s23, s21, 0x4400
	s_mulk_i32 s21, 0x4400
	s_add_u32 s22, s17, s21
	s_addc_u32 s23, s18, s23
	v_lshl_add_u64 v[64:65], s[14:15], 0, v[210:211]
	v_lshl_add_u64 v[72:73], s[14:15], 0, v[212:213]
	v_lshl_add_u64 v[80:81], s[14:15], 0, v[214:215]
	v_lshl_add_u64 v[88:89], s[14:15], 0, v[216:217]
	s_add_u32 s14, s22, 0x2000
	v_lshl_add_u64 v[68:69], s[12:13], 0, v[210:211]
	v_lshl_add_u64 v[76:77], s[12:13], 0, v[212:213]
	v_lshl_add_u64 v[84:85], s[12:13], 0, v[214:215]
	v_lshl_add_u64 v[92:93], s[12:13], 0, v[216:217]
	s_addc_u32 s15, s23, 0
	v_lshl_add_u64 v[104:105], s[22:23], 0, v[210:211]
	global_load_dwordx4 v[64:67], v[64:65], off
	s_nop 0
	global_load_dwordx4 v[68:71], v[68:69], off
	s_nop 0
	global_load_dwordx4 v[72:75], v[72:73], off
	s_nop 0
	global_load_dwordx4 v[76:79], v[76:77], off
	s_nop 0
	global_load_dwordx4 v[80:83], v[80:81], off
	s_nop 0
	global_load_dwordx4 v[84:87], v[84:85], off
	s_nop 0
	global_load_dwordx4 v[88:91], v[88:89], off
	s_nop 0
	global_load_dwordx4 v[92:95], v[92:93], off
	v_lshl_add_u64 v[106:107], s[14:15], 0, v[210:211]
	global_load_dwordx4 v[120:123], v[104:105], off
	global_load_dwordx4 v[124:127], v[106:107], off
	v_lshl_add_u64 v[104:105], s[22:23], 0, v[212:213]
	v_lshl_add_u64 v[106:107], s[14:15], 0, v[212:213]
	global_load_dwordx4 v[128:131], v[104:105], off
	global_load_dwordx4 v[132:135], v[106:107], off
	v_lshl_add_u64 v[104:105], v[152:153], 2, s[22:23]
	v_add_co_u32_e32 v104, vcc, s6, v104
	v_add_u32_e32 v137, 0x4000, v158
	s_nop 0
	v_addc_co_u32_e32 v105, vcc, 0, v105, vcc
	global_load_dword v136, v[104:105], off
	v_lshl_add_u64 v[104:105], v[154:155], 1, s[12:13]
	v_lshl_add_u64 v[104:105], v[104:105], 0, v[156:157]
	v_lshl_add_u64 v[106:107], v[104:105], 0, s[10:11]
	v_add_co_u32_e32 v104, vcc, s20, v104
	v_add_u32_e32 v138, 0x4000, v160
	s_nop 0
	v_addc_co_u32_e32 v105, vcc, 0, v105, vcc
	global_load_dwordx2 v[118:119], v[104:105], off
	global_load_dwordx2 v[116:117], v[106:107], off offset:64
	global_load_dwordx2 v[112:113], v[106:107], off offset:80
	global_load_dwordx2 v[108:109], v[106:107], off offset:96
	s_nop 0
	global_load_dwordx2 v[104:105], v[106:107], off offset:112
	global_load_dwordx2 v[114:115], v[106:107], off offset:16
	global_load_dwordx2 v[110:111], v[106:107], off offset:32
	s_nop 0
	global_load_dwordx2 v[106:107], v[106:107], off offset:48
	v_add_u32_e32 v139, 0x4000, v162
	v_add_u32_e32 v140, 0x4000, v164
	v_add_u32_e32 v141, 0x8800, v166
	v_add_u32_e32 v142, 0xa800, v166
	v_add_u32_e32 v143, 0x8800, v168
	v_add_u32_e32 v144, 0xa800, v168
	s_waitcnt vmcnt(20)
	ds_write2_b64 v158, v[64:65], v[66:67] offset1:2
	s_waitcnt vmcnt(19)
	ds_write2_b64 v137, v[68:69], v[70:71] offset0:128 offset1:130
	s_waitcnt vmcnt(18)
	ds_write2_b64 v160, v[72:73], v[74:75] offset1:2
	s_waitcnt vmcnt(17)
	ds_write2_b64 v138, v[76:77], v[78:79] offset0:128 offset1:130
	s_waitcnt vmcnt(16)
	ds_write2_b64 v162, v[80:81], v[82:83] offset1:2
	s_waitcnt vmcnt(15)
	ds_write2_b64 v139, v[84:85], v[86:87] offset0:128 offset1:130
	s_waitcnt vmcnt(14)
	ds_write2_b64 v164, v[88:89], v[90:91] offset1:2
	s_waitcnt vmcnt(13)
	ds_write2_b64 v140, v[92:93], v[94:95] offset0:128 offset1:130
	s_waitcnt vmcnt(12)
	ds_write2_b64 v141, v[120:121], v[122:123] offset1:2
	s_waitcnt vmcnt(11)
	ds_write2_b64 v142, v[124:125], v[126:127] offset0:128 offset1:130
	s_waitcnt vmcnt(10)
	ds_write2_b64 v143, v[128:129], v[130:131] offset1:2
	s_waitcnt vmcnt(9)
	ds_write2_b64 v144, v[132:133], v[134:135] offset0:128 offset1:130
	s_waitcnt vmcnt(8)
	ds_write_b32 v221, v136 offset:53248
	s_waitcnt lgkmcnt(0)
	s_barrier
	ds_read_b128 v[64:67], v223
	ds_read_b128 v[128:131], v223 offset:32
	v_cvt_pk_bf16_f32 v120, v48, v49
	v_cvt_pk_bf16_f32 v121, v50, v51
	v_cvt_pk_bf16_f32 v122, v52, v53
	v_cvt_pk_bf16_f32 v123, v54, v55
	ds_read_b128 v[80:83], v223 offset:8704
	ds_read_b128 v[132:135], v223 offset:8736
	v_cvt_pk_bf16_f32 v124, v56, v57
	v_cvt_pk_bf16_f32 v125, v58, v59
	s_waitcnt lgkmcnt(3)
	v_mfma_f32_32x32x16_bf16 v[64:79], v[64:67], v[120:123], 0
	v_cvt_pk_bf16_f32 v126, v60, v61
	v_cvt_pk_bf16_f32 v127, v62, v63
	v_cvt_pk_bf16_f32 v136, v40, v41
	v_cvt_pk_bf16_f32 v137, v42, v43
	v_cvt_pk_bf16_f32 v138, v44, v45
	v_cvt_pk_bf16_f32 v139, v46, v47
	v_cvt_pk_bf16_f32 v148, v24, v25
	s_waitcnt lgkmcnt(1)
	v_mfma_f32_32x32x16_bf16 v[80:95], v[80:83], v[120:123], 0
	ds_read_b128 v[140:143], v223 offset:96
	v_cvt_pk_bf16_f32 v149, v26, v27
	v_cvt_pk_bf16_f32 v150, v28, v29
	v_cvt_pk_bf16_f32 v151, v30, v31
	s_waitcnt vmcnt(7)
	v_lshlrev_b32_e32 v163, 16, v118
	v_and_b32_e32 v118, 0xffff0000, v118
	v_mfma_f32_32x32x16_bf16 v[64:79], v[128:131], v[124:127], v[64:79]
	ds_read_b128 v[128:131], v223 offset:64
	s_waitcnt lgkmcnt(2)
	v_mfma_f32_32x32x16_bf16 v[80:95], v[132:135], v[124:127], v[80:95]
	v_cvt_pk_bf16_f32 v132, v32, v33
	v_cvt_pk_bf16_f32 v133, v34, v35
	v_cvt_pk_bf16_f32 v134, v36, v37
	v_cvt_pk_bf16_f32 v135, v38, v39
	s_waitcnt lgkmcnt(0)
	s_nop 0
	v_mfma_f32_32x32x16_bf16 v[64:79], v[128:131], v[132:135], v[64:79]
	ds_read_b128 v[128:131], v223 offset:8768
	ds_read_b128 v[144:147], v223 offset:8800
	s_waitcnt lgkmcnt(1)
	v_mfma_f32_32x32x16_bf16 v[80:95], v[128:131], v[132:135], v[80:95]
	ds_read_b128 v[128:131], v223 offset:128
	v_mfma_f32_32x32x16_bf16 v[64:79], v[140:143], v[136:139], v[64:79]
	v_cvt_pk_bf16_f32 v140, v16, v17
	v_cvt_pk_bf16_f32 v141, v18, v19
	v_cvt_pk_bf16_f32 v142, v20, v21
	v_cvt_pk_bf16_f32 v143, v22, v23
	s_waitcnt lgkmcnt(1)
; __device__ __forceinline__ unsigned cvtpk(float lo, float hi) { f32x2_t v = {lo, hi}; bf16x2_t b = __builtin_convertvector(v, bf16x2_t); return __builtin_bit_cast(unsigned, b); }
; __device__ __forceinline__ float bflo(unsigned v) { return __uint_as_float(v << 16); }
; __device__ __forceinline__ float bfhi(unsigned v) { return __uint_as_float(v & 0xffff0000u); }
; __device__ __forceinline__ f32x16 mfma32(bf16x8 a, bf16x8 b, f32x16 c) { return __builtin_amdgcn_mfma_f32_32x32x16_bf16(a, b, c, 0, 0, 0); }
; __device__ __forceinline__ void scan_chunked(const Params& p, unsigned char* smem, int bh, f32x16 (&S)[4], const int c_begin, const int c_end) {
;     ...
;           const bf16x8 k0f = *(const bf16x8*)(sk + (l31) * 136 + 32 * dt + 16 * s + 8 * hf);
;           const bf16x8 k1f = *(const bf16x8*)(sk + (32 + l31) * 136 + 32 * dt + 16 * s + 8 * hf);
;           x0 = mfma32(k0f, __builtin_bit_cast(bf16x8, sb), x0);
;           x1 = mfma32(k1f, __builtin_bit_cast(bf16x8, sb), x1);
;         }
; #pragma unroll
;       for (int g = 0; g < 4; ++g) {
;         {
;           float4 bg4 = *(const float4*)(sSC + 64 + 8 * g + 4 * hf);
;           uint2 vb = pv[g];
;           yf[(g >> 1)][(g & 1) * 2 + 0] = cvtpk(bflo(vb.x) - bg4.x * x0[4 * g + 0], bfhi(vb.x) - bg4.y * x0[4 * g + 1]);
;           yf[(g >> 1)][(g & 1) * 2 + 1] = cvtpk(bflo(vb.y) - bg4.z * x0[4 * g + 2], bfhi(vb.y) - bg4.w * x0[4 * g + 3]);
;         }
;         {
;           float4 bg4 = *(const float4*)(sSC + 64 + 32 + 8 * g + 4 * hf);
;           uint2 vb = pv[4 + g];
;           yf[2 + (g >> 1)][(g & 1) * 2 + 0] = cvtpk(bflo(vb.x) - bg4.x * x1[4 * g + 0], bfhi(vb.x) - bg4.y * x1[4 * g + 1]);
;           yf[2 + (g >> 1)][(g & 1) * 2 + 1] = cvtpk(bflo(vb.y) - bg4.z * x1[4 * g + 2], bfhi(vb.y) - bg4.w * x1[4 * g + 3]);
;         }
;       }
;     }
;     __builtin_amdgcn_sched_barrier(0);
;     u32x4 vnf[4];
;     {
;       f32x16 v0, v1;
; #pragma unroll
;       for (int r = 0; r < 16; ++r) { v0[r] = 0.f; v1[r] = 0.f; }
; #pragma unroll
;       for (int s = 0; s < 4; ++s) {
;         const bf16x8 t0f = *(const bf16x8*)(sT + (l31) * 72 + 16 * s + 8 * hf);
;         const bf16x8 t1f = *(const bf16x8*)(sT + (32 + l31) * 72 + 16 * s + 8 * hf);
;         v0 = mfma32(t0f, __builtin_bit_cast(bf16x8, yf[s]), v0);
;         v1 = mfma32(t1f, __builtin_bit_cast(bf16x8, yf[s]), v1);
;       }
	v_mfma_f32_32x32x16_bf16 v[80:95], v[144:147], v[136:139], v[80:95]
	ds_read_b128 v[144:147], v223 offset:160
	s_waitcnt lgkmcnt(1)
	v_mfma_f32_32x32x16_bf16 v[64:79], v[128:131], v[140:143], v[64:79]
	ds_read_b128 v[128:131], v223 offset:8832
	ds_read_b128 v[226:229], v223 offset:8864
	s_waitcnt lgkmcnt(1)
	v_mfma_f32_32x32x16_bf16 v[80:95], v[128:131], v[140:143], v[80:95]
	ds_read_b128 v[128:131], v223 offset:192
	v_mfma_f32_32x32x16_bf16 v[64:79], v[144:147], v[148:151], v[64:79]
	v_cvt_pk_bf16_f32 v144, v0, v1
	v_cvt_pk_bf16_f32 v145, v2, v3
	v_cvt_pk_bf16_f32 v146, v4, v5
	v_cvt_pk_bf16_f32 v147, v6, v7
	s_waitcnt lgkmcnt(1)
	v_mfma_f32_32x32x16_bf16 v[80:95], v[226:229], v[148:151], v[80:95]
	ds_read_b128 v[226:229], v223 offset:224
	ds_read_b128 v[230:233], v223 offset:8896
	ds_read_b128 v[234:237], v223 offset:8928
	ds_read_b128 v[238:241], v222 offset:53504
	s_waitcnt lgkmcnt(4)
	v_mfma_f32_32x32x16_bf16 v[64:79], v[128:131], v[144:147], v[64:79]
	v_cvt_pk_bf16_f32 v128, v8, v9
	v_cvt_pk_bf16_f32 v129, v10, v11
	v_cvt_pk_bf16_f32 v130, v12, v13
	v_cvt_pk_bf16_f32 v131, v14, v15
	s_waitcnt lgkmcnt(2)
	v_mfma_f32_32x32x16_bf16 v[80:95], v[230:233], v[144:147], v[80:95]
	v_mfma_f32_32x32x16_bf16 v[64:79], v[226:229], v[128:131], v[64:79]
	ds_read_b128 v[226:229], v222 offset:53536
	s_waitcnt lgkmcnt(2)
	v_mfma_f32_32x32x16_bf16 v[80:95], v[234:237], v[128:131], v[80:95]
	s_waitcnt lgkmcnt(1)
	s_nop 7
	v_fma_f32 v64, -v64, v238, v163
	v_fma_f32 v65, -v65, v239, v118
	v_cvt_pk_bf16_f32 v238, v64, v65
	v_lshlrev_b32_e32 v64, 16, v119
	v_and_b32_e32 v65, 0xffff0000, v119
	v_fma_f32 v64, -v66, v240, v64
	v_fma_f32 v65, -v67, v241, v65
	v_cvt_pk_bf16_f32 v239, v64, v65
	ds_read_b128 v[64:67], v222 offset:53632
	ds_read_b128 v[230:233], v222 offset:53664
	s_waitcnt vmcnt(6)
	v_lshlrev_b32_e32 v118, 16, v116
	s_waitcnt lgkmcnt(1)
	v_fma_f32 v64, -v80, v64, v118
	v_and_b32_e32 v80, 0xffff0000, v116
	v_fma_f32 v65, -v81, v65, v80
	v_cvt_pk_bf16_f32 v116, v64, v65
	v_lshlrev_b32_e32 v64, 16, v117
	v_and_b32_e32 v65, 0xffff0000, v117
	v_fma_f32 v64, -v82, v66, v64
	v_fma_f32 v65, -v83, v67, v65
	v_cvt_pk_bf16_f32 v117, v64, v65
	s_waitcnt vmcnt(2)
	v_lshlrev_b32_e32 v64, 16, v114
	v_and_b32_e32 v65, 0xffff0000, v114
	v_fma_f32 v64, -v68, v226, v64
	v_fma_f32 v65, -v69, v227, v65
	v_cvt_pk_bf16_f32 v240, v64, v65
	v_lshlrev_b32_e32 v64, 16, v115
	v_and_b32_e32 v65, 0xffff0000, v115
	v_fma_f32 v64, -v70, v228, v64
	v_fma_f32 v65, -v71, v229, v65
	v_cvt_pk_bf16_f32 v241, v64, v65
	v_lshlrev_b32_e32 v64, 16, v112
	v_and_b32_e32 v65, 0xffff0000, v112
	s_waitcnt lgkmcnt(0)
	v_fma_f32 v64, -v84, v230, v64
	v_fma_f32 v65, -v85, v231, v65
	v_cvt_pk_bf16_f32 v118, v64, v65
	v_lshlrev_b32_e32 v64, 16, v113
	v_fma_f32 v68, -v86, v232, v64
	ds_read_b128 v[64:67], v222 offset:53568
	v_and_b32_e32 v69, 0xffff0000, v113
	v_fma_f32 v69, -v87, v233, v69
	s_waitcnt vmcnt(1)
	v_lshlrev_b32_e32 v80, 16, v110
	v_cvt_pk_bf16_f32 v119, v68, v69
	ds_read_b128 v[68:71], v222 offset:53600
	s_waitcnt lgkmcnt(1)
	v_fma_f32 v64, -v72, v64, v80
	ds_read_b128 v[80:83], v222 offset:53696
	v_and_b32_e32 v72, 0xffff0000, v110
	v_fma_f32 v65, -v73, v65, v72
	v_cvt_pk_bf16_f32 v110, v64, v65
	v_lshlrev_b32_e32 v64, 16, v111
	v_and_b32_e32 v65, 0xffff0000, v111
	v_fma_f32 v64, -v74, v66, v64
	v_fma_f32 v65, -v75, v67, v65
	v_lshlrev_b32_e32 v72, 16, v108
	v_and_b32_e32 v73, 0xffff0000, v108
	v_cvt_pk_bf16_f32 v111, v64, v65
	ds_read_b128 v[64:67], v222 offset:53728
	s_waitcnt lgkmcnt(1)
	v_fma_f32 v72, -v88, v80, v72
	v_fma_f32 v73, -v89, v81, v73
	v_cvt_pk_bf16_f32 v226, v72, v73
	v_lshlrev_b32_e32 v72, 16, v109
	v_and_b32_e32 v73, 0xffff0000, v109
	v_fma_f32 v72, -v90, v82, v72
	v_fma_f32 v73, -v91, v83, v73
	v_cvt_pk_bf16_f32 v227, v72, v73
	s_waitcnt vmcnt(0)
	v_lshlrev_b32_e32 v72, 16, v106
	v_fma_f32 v68, -v76, v68, v72
	v_and_b32_e32 v72, 0xffff0000, v106
	v_fma_f32 v69, -v77, v69, v72
	v_cvt_pk_bf16_f32 v112, v68, v69
	v_lshlrev_b32_e32 v68, 16, v107
	v_and_b32_e32 v69, 0xffff0000, v107
	v_fma_f32 v68, -v78, v70, v68
	v_fma_f32 v69, -v79, v71, v69
	v_cvt_pk_bf16_f32 v113, v68, v69
	v_lshlrev_b32_e32 v68, 16, v104
	s_waitcnt lgkmcnt(0)
	v_fma_f32 v64, -v92, v64, v68
	v_and_b32_e32 v68, 0xffff0000, v104
	v_fma_f32 v65, -v93, v65, v68
	v_cvt_pk_bf16_f32 v228, v64, v65
	v_lshlrev_b32_e32 v64, 16, v105
	v_and_b32_e32 v65, 0xffff0000, v105
	v_fma_f32 v64, -v94, v66, v64
	v_fma_f32 v65, -v95, v67, v65
	v_cvt_pk_bf16_f32 v229, v64, v65
	ds_read_b128 v[64:67], v224 offset:34816
	ds_read_b128 v[104:107], v224 offset:34848
	ds_read_b128 v[80:83], v224 offset:39424
	ds_read_b128 v[230:233], v224 offset:39456
	s_waitcnt lgkmcnt(3)
	v_mfma_f32_32x32x16_bf16 v[64:79], v[64:67], v[238:241], 0
	s_waitcnt lgkmcnt(1)
	v_mfma_f32_32x32x16_bf16 v[80:95], v[80:83], v[238:241], 0
	v_mfma_f32_32x32x16_bf16 v[64:79], v[104:107], v[110:113], v[64:79]
	s_waitcnt lgkmcnt(0)
	v_mfma_f32_32x32x16_bf16 v[80:95], v[230:233], v[110:113], v[80:95]
	ds_read_b128 v[104:107], v224 offset:34880
	ds_read_b128 v[108:111], v224 offset:34912
	s_waitcnt lgkmcnt(1)
	v_mfma_f32_32x32x16_bf16 v[64:79], v[104:107], v[116:119], v[64:79]
	ds_read_b128 v[104:107], v224 offset:39488
	ds_read_b128 v[112:115], v224 offset:39520
	s_waitcnt lgkmcnt(1)
	v_mfma_f32_32x32x16_bf16 v[80:95], v[104:107], v[116:119], v[80:95]
	v_mfma_f32_32x32x16_bf16 v[64:79], v[108:111], v[226:229], v[64:79]
	s_waitcnt lgkmcnt(0)
; __device__ __forceinline__ unsigned cvtpk(float lo, float hi) { f32x2_t v = {lo, hi}; bf16x2_t b = __builtin_convertvector(v, bf16x2_t); return __builtin_bit_cast(unsigned, b); }
; __device__ __forceinline__ void scan_chunked(const Params& p, unsigned char* smem, int bh, f32x16 (&S)[4], const int c_begin, const int c_end) {
;     ...
; #pragma unroll
;       for (int g = 0; g < 4; ++g) {
;         vnf[(g >> 1)][(g & 1) * 2 + 0] = cvtpk(v0[4 * g + 0], v0[4 * g + 1]);
;         vnf[(g >> 1)][(g & 1) * 2 + 1] = cvtpk(v0[4 * g + 2], v0[4 * g + 3]);
;         vnf[2 + (g >> 1)][(g & 1) * 2 + 0] = cvtpk(v1[4 * g + 0], v1[4 * g + 1]);
;         vnf[2 + (g >> 1)][(g & 1) * 2 + 1] = cvtpk(v1[4 * g + 2], v1[4 * g + 3]);
;       }
;     }
;     __builtin_amdgcn_sched_barrier(0);
;     u16* Oq = DX + ((size_t)(bh * NCH + c) * 3) * 8192;
;     {
;       f32x16 o0, o1;
; #pragma unroll
;       for (int r = 0; r < 16; ++r) { o0[r] = 0.f; o1[r] = 0.f; }
; #pragma unroll
;       for (int dt = 0; dt < 4; ++dt)
; #pragma unroll
;         for (int s = 0; s < 2; ++s) {
;           u32x4 sb = {cvtpk(S[dt][8 * s + 0], S[dt][8 * s + 1]), cvtpk(S[dt][8 * s + 2], S[dt][8 * s + 3]), cvtpk(S[dt][8 * s + 4], S[dt][8 * s + 5]), cvtpk(S[dt][8 * s + 6], S[dt][8 * s + 7])};
;           const bf16x8 q0f = *(const bf16x8*)(sq + (l31) * 136 + 32 * dt + 16 * s + 8 * hf);
;           const bf16x8 q1f = *(const bf16x8*)(sq + (32 + l31) * 136 + 32 * dt + 16 * s + 8 * hf);
;           o0 = mfma32(q0f, __builtin_bit_cast(bf16x8, sb), o0);
;           o1 = mfma32(q1f, __builtin_bit_cast(bf16x8, sb), o1);
;         }
; #pragma unroll
;       for (int g = 0; g < 4; ++g) {
;         float4 e0 = *(const float4*)(sSC + 128 + 8 * g + 4 * hf), e1 = *(const float4*)(sSC + 128 + 32 + 8 * g + 4 * hf);
;         o0[4 * g + 0] *= e0.x; o0[4 * g + 1] *= e0.y; o0[4 * g + 2] *= e0.z; o0[4 * g + 3] *= e0.w;
;         o1[4 * g + 0] *= e1.x; o1[4 * g + 1] *= e1.y; o1[4 * g + 2] *= e1.z; o1[4 * g + 3] *= e1.w;
;       }
; #pragma unroll
;       for (int s = 0; s < 4; ++s) {
;         const bf16x8 a0f = *(const bf16x8*)(sA + (l31) * 72 + 16 * s + 8 * hf);
;         const bf16x8 a1f = *(const bf16x8*)(sA + (32 + l31) * 72 + 16 * s + 8 * hf);
;         o0 = mfma32(a0f, __builtin_bit_cast(bf16x8, vnf[s]), o0);
;         o1 = mfma32(a1f, __builtin_bit_cast(bf16x8, vnf[s]), o1);
;       }
	v_mfma_f32_32x32x16_bf16 v[80:95], v[112:115], v[226:229], v[80:95]
	s_nop 9
	v_cvt_pk_bf16_f32 v116, v64, v65
	v_cvt_pk_bf16_f32 v117, v66, v67
	v_cvt_pk_bf16_f32 v118, v68, v69
	v_cvt_pk_bf16_f32 v119, v70, v71
	v_cvt_pk_bf16_f32 v112, v72, v73
	v_cvt_pk_bf16_f32 v113, v74, v75
	v_cvt_pk_bf16_f32 v114, v76, v77
	v_cvt_pk_bf16_f32 v108, v80, v81
	v_cvt_pk_bf16_f32 v109, v82, v83
	v_cvt_pk_bf16_f32 v110, v84, v85
	v_cvt_pk_bf16_f32 v111, v86, v87
	v_cvt_pk_bf16_f32 v104, v88, v89
	v_cvt_pk_bf16_f32 v105, v90, v91
	v_cvt_pk_bf16_f32 v115, v78, v79
	v_cvt_pk_bf16_f32 v106, v92, v93
	v_cvt_pk_bf16_f32 v107, v94, v95
	ds_read_b128 v[64:67], v223 offset:17408
	ds_read_b128 v[226:229], v223 offset:17440
	ds_read_b128 v[80:83], v223 offset:26112
	ds_read_b128 v[230:233], v223 offset:26144
	s_waitcnt lgkmcnt(3)
	v_mfma_f32_32x32x16_bf16 v[64:79], v[64:67], v[120:123], 0
	s_waitcnt lgkmcnt(1)
	v_mfma_f32_32x32x16_bf16 v[80:95], v[80:83], v[120:123], 0
	v_mfma_f32_32x32x16_bf16 v[64:79], v[226:229], v[124:127], v[64:79]
	s_waitcnt lgkmcnt(0)
	v_mfma_f32_32x32x16_bf16 v[80:95], v[230:233], v[124:127], v[80:95]
	ds_read_b128 v[120:123], v223 offset:17472
	ds_read_b128 v[124:127], v223 offset:17504
	s_waitcnt lgkmcnt(1)
	v_mfma_f32_32x32x16_bf16 v[64:79], v[120:123], v[132:135], v[64:79]
	ds_read_b128 v[120:123], v223 offset:26176
	ds_read_b128 v[226:229], v223 offset:26208
	s_waitcnt lgkmcnt(1)
	v_mfma_f32_32x32x16_bf16 v[80:95], v[120:123], v[132:135], v[80:95]
	v_mfma_f32_32x32x16_bf16 v[64:79], v[124:127], v[136:139], v[64:79]
	ds_read_b128 v[120:123], v223 offset:17536
	ds_read_b128 v[124:127], v223 offset:17568
	s_waitcnt lgkmcnt(2)
	v_mfma_f32_32x32x16_bf16 v[80:95], v[226:229], v[136:139], v[80:95]
	s_waitcnt lgkmcnt(1)
	v_mfma_f32_32x32x16_bf16 v[64:79], v[120:123], v[140:143], v[64:79]
	ds_read_b128 v[120:123], v223 offset:26240
	ds_read_b128 v[132:135], v223 offset:26272
	s_waitcnt lgkmcnt(1)
	v_mfma_f32_32x32x16_bf16 v[80:95], v[120:123], v[140:143], v[80:95]
	v_mfma_f32_32x32x16_bf16 v[64:79], v[124:127], v[148:151], v[64:79]
	ds_read_b128 v[120:123], v223 offset:17600
	ds_read_b128 v[124:127], v223 offset:17632
	s_waitcnt lgkmcnt(2)
	v_mfma_f32_32x32x16_bf16 v[80:95], v[132:135], v[148:151], v[80:95]
	s_waitcnt lgkmcnt(1)
	v_mfma_f32_32x32x16_bf16 v[64:79], v[120:123], v[144:147], v[64:79]
	ds_read_b128 v[120:123], v223 offset:26304
	ds_read_b128 v[132:135], v223 offset:26336
	s_waitcnt lgkmcnt(1)
	v_mfma_f32_32x32x16_bf16 v[80:95], v[120:123], v[144:147], v[80:95]
	v_mfma_f32_32x32x16_bf16 v[64:79], v[124:127], v[128:131], v[64:79]
	ds_read_b128 v[124:127], v222 offset:53824
	ds_read_b128 v[136:139], v222 offset:53856
	ds_read_b128 v[140:143], v222 offset:53760
	ds_read_b128 v[148:151], v222 offset:53792
	ds_read_b128 v[226:229], v222 offset:53888
	ds_read_b128 v[230:233], v222 offset:53920
	s_waitcnt lgkmcnt(4)
	s_nop 4
	v_pk_mul_f32 v[78:79], v[78:79], v[138:139]
	v_mfma_f32_32x32x16_bf16 v[80:95], v[132:135], v[128:131], v[80:95]
	v_mul_f32_e64 v76, v76, v136
	v_mul_f32_e64 v77, v77, v137
	v_mul_f32_e64 v74, v74, v126
	v_mul_f32_e64 v75, v75, v127
	v_mul_f32_e64 v72, v72, v124
	v_mul_f32_e64 v73, v73, v125
	ds_read_b128 v[120:123], v222 offset:53952
	ds_read_b128 v[124:127], v222 offset:53984
	ds_read_b128 v[136:139], v224 offset:44032
	s_waitcnt lgkmcnt(5)
	v_pk_mul_f32 v[70:71], v[70:71], v[150:151]
	v_pk_mul_f32 v[68:69], v[68:69], v[148:149]
	v_pk_mul_f32 v[66:67], v[66:67], v[142:143]
	v_pk_mul_f32 v[64:65], v[64:65], v[140:141]
	s_waitcnt lgkmcnt(1)
	v_pk_mul_f32 v[94:95], v[94:95], v[126:127]
	v_pk_mul_f32 v[92:93], v[92:93], v[124:125]
	ds_read_b128 v[124:127], v224 offset:48640
	ds_read_b128 v[128:131], v224 offset:44064
	s_waitcnt lgkmcnt(2)
	v_mfma_f32_32x32x16_bf16 v[64:79], v[136:139], v[116:119], v[64:79]
	v_mul_f32_e64 v90, v90, v122
	v_mul_f32_e64 v91, v91, v123
	v_mul_f32_e64 v88, v88, v120
	v_mul_f32_e64 v89, v89, v121
	v_mul_f32_e64 v86, v86, v232
	v_mul_f32_e64 v87, v87, v233
	v_pk_mul_f32 v[84:85], v[84:85], v[230:231]
	v_pk_mul_f32 v[82:83], v[82:83], v[228:229]
	v_pk_mul_f32 v[80:81], v[80:81], v[226:227]
	ds_read_b128 v[120:123], v224 offset:48672
	s_waitcnt lgkmcnt(1)
	v_mfma_f32_32x32x16_bf16 v[64:79], v[128:131], v[112:115], v[64:79]
	v_mfma_f32_32x32x16_bf16 v[80:95], v[124:127], v[116:119], v[80:95]
	s_waitcnt lgkmcnt(0)
	v_mfma_f32_32x32x16_bf16 v[80:95], v[120:123], v[112:115], v[80:95]
	ds_read_b128 v[120:123], v224 offset:44096
	ds_read_b128 v[124:127], v224 offset:44128
	s_waitcnt lgkmcnt(1)
	v_mfma_f32_32x32x16_bf16 v[64:79], v[120:123], v[108:111], v[64:79]
	ds_read_b128 v[120:123], v224 offset:48704
	ds_read_b128 v[128:131], v224 offset:48736
	s_waitcnt lgkmcnt(1)
	v_mfma_f32_32x32x16_bf16 v[80:95], v[120:123], v[108:111], v[80:95]
	v_lshl_add_u64 v[120:121], v[170:171], 1, s[12:13]
	v_mfma_f32_32x32x16_bf16 v[64:79], v[124:127], v[104:107], v[64:79]
	s_waitcnt lgkmcnt(0)
; __device__ __forceinline__ u16 f2bf(float f) { return (u16)(cvtpk(f, 0.f) & 0xffffu); }
; __device__ __forceinline__ void scan_chunked(const Params& p, unsigned char* smem, int bh, f32x16 (&S)[4], const int c_begin, const int c_end) {
;     ...
; #pragma unroll
;       for (int r = 0; r < 16; ++r) {
;         Oq[(8 * (r >> 2) + 4 * hf + (r & 3)) * 128 + wave * 32 + l31] = f2bf(o0[r]);
;         Oq[(32 + 8 * (r >> 2) + 4 * hf + (r & 3)) * 128 + wave * 32 + l31] = f2bf(o1[r]);
;       }
;     }
;     __builtin_amdgcn_sched_barrier(0);
;     const float cd = sSC[128 + 63];
; #pragma unroll
;     for (int dt = 0; dt < 4; ++dt)
; #pragma unroll
;       for (int r = 0; r < 16; ++r) S[dt][r] *= cd;
;     u32x4 vs[4];
; #pragma unroll
;     for (int s = 0; s < 4; ++s) {
;       const float4 e0 = *(const float4*)(sSC + 192 + 16 * s + 4 * hf), e1 = *(const float4*)(sSC + 192 + 16 * s + 8 + 4 * hf);
;       vs[s].x = cvtpk(bflo(vnf[s].x) * e0.x, bfhi(vnf[s].x) * e0.y); vs[s].y = cvtpk(bflo(vnf[s].y) * e0.z, bfhi(vnf[s].y) * e0.w);
;       vs[s].z = cvtpk(bflo(vnf[s].z) * e1.x, bfhi(vnf[s].z) * e1.y); vs[s].w = cvtpk(bflo(vnf[s].w) * e1.z, bfhi(vnf[s].w) * e1.w);
;     }
;     {
;       u32x4 id1 = {0u, 0u, 0u, 0u}, id2 = {0u, 0u, 0u, 0u};
;       {
;         const int l15 = l31 & 15;
;         const int jsel = (((l15 >> 2) & 1) == hf) ? (4 * (l15 >> 3) + (l15 & 3)) : -1;
;         const int j1 = (l31 < 16) ? jsel : -1;
;         const int j2 = (l31 >= 16) ? jsel : -1;
;         const unsigned one_lo = 0x3f80u, one_hi = 0x3f800000u;
; #pragma unroll
;         for (int w = 0; w < 4; ++w) {
;           id1[w] = (j1 == 2 * w) ? one_lo : ((j1 == 2 * w + 1) ? one_hi : 0u);
;           id2[w] = (j2 == 2 * w) ? one_lo : ((j2 == 2 * w + 1) ? one_hi : 0u);
;         }
;       }
;       const bf16x8 B1 = __builtin_bit_cast(bf16x8, id1), B2 = __builtin_bit_cast(bf16x8, id2);
; #pragma unroll
;       for (int dt = 0; dt < 4; ++dt)
; #pragma unroll
;         for (int mt = 0; mt < 2; ++mt) {
;           f32x16 kt;
; #pragma unroll
;           for (int r = 0; r < 16; ++r) kt[r] = 0.f;
;           const u16* k0 = sk + (32 * mt + l31) * 136 + 32 * dt + 8 * hf;
;           kt = mfma32(*(const bf16x8*)(k0), B1, kt);
;           kt = mfma32(*(const bf16x8*)(k0 + 16), B2, kt);
; #pragma unroll
;           for (int s2 = 0; s2 < 2; ++s2) {
	v_mfma_f32_32x32x16_bf16 v[80:95], v[128:131], v[104:107], v[80:95]
	s_nop 9
	v_cvt_pk_bf16_f32 v64, v64, s0
	global_store_short v[120:121], v64, off
	v_lshl_add_u64 v[120:121], v[172:173], 1, s[12:13]
	v_cvt_pk_bf16_f32 v66, v66, s0
	v_cvt_pk_bf16_f32 v64, v80, s0
	global_store_short v[120:121], v64, off
	v_cvt_pk_bf16_f32 v80, v65, s0
	v_lshl_add_u64 v[64:65], v[206:207], 1, s[12:13]
	global_store_short v[64:65], v80, off offset:256
	v_cvt_pk_bf16_f32 v120, v81, s0
	v_lshl_add_u64 v[80:81], v[208:209], 1, s[12:13]
	global_store_short v[80:81], v120, off offset:256
	global_store_short v[64:65], v66, off offset:512
	v_cvt_pk_bf16_f32 v66, v82, s0
	global_store_short v[80:81], v66, off offset:512
	v_cvt_pk_bf16_f32 v66, v67, s0
	global_store_short v[64:65], v66, off offset:768
	v_cvt_pk_bf16_f32 v66, v83, s0
	global_store_short v[80:81], v66, off offset:768
	v_cvt_pk_bf16_f32 v66, v68, s0
	global_store_short v[64:65], v66, off offset:2048
	v_cvt_pk_bf16_f32 v66, v84, s0
	global_store_short v[80:81], v66, off offset:2048
	v_cvt_pk_bf16_f32 v66, v69, s0
	global_store_short v[64:65], v66, off offset:2304
	v_cvt_pk_bf16_f32 v66, v85, s0
	global_store_short v[80:81], v66, off offset:2304
	v_cvt_pk_bf16_f32 v66, v70, s0
	global_store_short v[64:65], v66, off offset:2560
	v_cvt_pk_bf16_f32 v66, v86, s0
	global_store_short v[80:81], v66, off offset:2560
	v_cvt_pk_bf16_f32 v66, v71, s0
	global_store_short v[64:65], v66, off offset:2816
	v_cvt_pk_bf16_f32 v64, v87, s0
	global_store_short v[80:81], v64, off offset:2816
	v_cvt_pk_bf16_f32 v66, v72, s0
	v_lshl_add_u64 v[64:65], v[174:175], 1, s[12:13]
	global_store_short v[64:65], v66, off
	v_cvt_pk_bf16_f32 v66, v88, s0
	v_lshl_add_u64 v[64:65], v[176:177], 1, s[12:13]
	global_store_short v[64:65], v66, off
	v_cvt_pk_bf16_f32 v66, v73, s0
	v_lshl_add_u64 v[64:65], v[178:179], 1, s[12:13]
	global_store_short v[64:65], v66, off
	v_cvt_pk_bf16_f32 v66, v89, s0
	v_lshl_add_u64 v[64:65], v[180:181], 1, s[12:13]
	global_store_short v[64:65], v66, off
	v_cvt_pk_bf16_f32 v66, v74, s0
	v_lshl_add_u64 v[64:65], v[182:183], 1, s[12:13]
	global_store_short v[64:65], v66, off
	v_cvt_pk_bf16_f32 v66, v90, s0
	v_lshl_add_u64 v[64:65], v[184:185], 1, s[12:13]
	global_store_short v[64:65], v66, off
	v_cvt_pk_bf16_f32 v66, v75, s0
	v_lshl_add_u64 v[64:65], v[186:187], 1, s[12:13]
	global_store_short v[64:65], v66, off
	v_cvt_pk_bf16_f32 v66, v91, s0
	v_lshl_add_u64 v[64:65], v[188:189], 1, s[12:13]
	global_store_short v[64:65], v66, off
	v_cvt_pk_bf16_f32 v66, v76, s0
	v_lshl_add_u64 v[64:65], v[190:191], 1, s[12:13]
	global_store_short v[64:65], v66, off
	v_cvt_pk_bf16_f32 v66, v92, s0
	v_lshl_add_u64 v[64:65], v[192:193], 1, s[12:13]
	global_store_short v[64:65], v66, off
	v_cvt_pk_bf16_f32 v66, v77, s0
	v_lshl_add_u64 v[64:65], v[194:195], 1, s[12:13]
	global_store_short v[64:65], v66, off
	v_cvt_pk_bf16_f32 v66, v93, s0
	v_lshl_add_u64 v[64:65], v[196:197], 1, s[12:13]
	global_store_short v[64:65], v66, off
	v_cvt_pk_bf16_f32 v66, v78, s0
	v_lshl_add_u64 v[64:65], v[198:199], 1, s[12:13]
	global_store_short v[64:65], v66, off
	v_cvt_pk_bf16_f32 v66, v94, s0
	v_lshl_add_u64 v[64:65], v[200:201], 1, s[12:13]
	global_store_short v[64:65], v66, off
	v_cvt_pk_bf16_f32 v66, v79, s0
	v_lshl_add_u64 v[64:65], v[202:203], 1, s[12:13]
	global_store_short v[64:65], v66, off
	v_cvt_pk_bf16_f32 v66, v95, s0
	v_lshl_add_u64 v[64:65], v[204:205], 1, s[12:13]
	global_store_short v[64:65], v66, off
	ds_read_b32 v92, v161 offset:54012
	ds_read_b128 v[226:229], v159
	ds_read_b128 v[230:233], v159 offset:32
	ds_read_b128 v[234:237], v159 offset:8704
	ds_read_b128 v[238:241], v159 offset:8736
	ds_read_b128 v[64:67], v222 offset:54016
	ds_read_b128 v[68:71], v222 offset:54048
	ds_read_b128 v[72:75], v222 offset:54080
	ds_read_b128 v[76:79], v222 offset:54112
	s_waitcnt lgkmcnt(7)
	v_mfma_f32_32x32x16_bf16 v[120:135], v[226:229], v[96:99], 0
	s_waitcnt lgkmcnt(6)
	v_mfma_f32_32x32x16_bf16 v[120:135], v[230:233], v[100:103], v[120:135]
	s_waitcnt lgkmcnt(5)
	v_mfma_f32_32x32x16_bf16 v[136:151], v[234:237], v[96:99], 0
	s_waitcnt lgkmcnt(4)
	v_mfma_f32_32x32x16_bf16 v[136:151], v[238:241], v[100:103], v[136:151]
	ds_read_b128 v[226:229], v159 offset:64
	ds_read_b128 v[230:233], v159 offset:96
	ds_read_b128 v[234:237], v159 offset:8768
	ds_read_b128 v[238:241], v159 offset:8800
	v_pk_mul_f32 v[62:63], v[62:63], v[92:93] op_sel_hi:[1,0]
	v_pk_mul_f32 v[60:61], v[60:61], v[92:93] op_sel_hi:[1,0]
	v_pk_mul_f32 v[58:59], v[58:59], v[92:93] op_sel_hi:[1,0]
	v_pk_mul_f32 v[56:57], v[56:57], v[92:93] op_sel_hi:[1,0]
	v_pk_mul_f32 v[54:55], v[54:55], v[92:93] op_sel_hi:[1,0]
	v_pk_mul_f32 v[52:53], v[52:53], v[92:93] op_sel_hi:[1,0]
	v_pk_mul_f32 v[50:51], v[50:51], v[92:93] op_sel_hi:[1,0]
	v_pk_mul_f32 v[48:49], v[48:49], v[92:93] op_sel_hi:[1,0]
	v_lshlrev_b32_e32 v242, 16, v116
	v_and_b32_e32 v243, 0xffff0000, v116
	s_waitcnt lgkmcnt(7)
	v_pk_mul_f32 v[242:243], v[64:65], v[242:243]
	v_cvt_pk_bf16_f32 v80, v242, v243
	v_lshlrev_b32_e32 v244, 16, v117
	v_and_b32_e32 v245, 0xffff0000, v117
	v_pk_mul_f32 v[244:245], v[66:67], v[244:245]
	v_cvt_pk_bf16_f32 v81, v244, v245
	v_lshlrev_b32_e32 v242, 16, v118
	v_and_b32_e32 v243, 0xffff0000, v118
	s_waitcnt lgkmcnt(6)
	v_pk_mul_f32 v[242:243], v[68:69], v[242:243]
	v_cvt_pk_bf16_f32 v82, v242, v243
	v_lshlrev_b32_e32 v244, 16, v119
	v_and_b32_e32 v245, 0xffff0000, v119
	v_pk_mul_f32 v[244:245], v[70:71], v[244:245]
	v_cvt_pk_bf16_f32 v83, v244, v245
	v_lshlrev_b32_e32 v242, 16, v112
	v_and_b32_e32 v243, 0xffff0000, v112
	s_waitcnt lgkmcnt(5)
; __device__ __forceinline__ float bflo(unsigned v) { return __uint_as_float(v << 16); }
; __device__ __forceinline__ void scan_chunked(const Params& p, unsigned char* smem, int bh, f32x16 (&S)[4], const int c_begin, const int c_end) {
;     ...
;     const float cd = sSC[128 + 63];
; #pragma unroll
;     for (int dt = 0; dt < 4; ++dt)
; #pragma unroll
;       for (int r = 0; r < 16; ++r) S[dt][r] *= cd;
;     u32x4 vs[4];
; #pragma unroll
;     for (int s = 0; s < 4; ++s) {
;       const float4 e0 = *(const float4*)(sSC + 192 + 16 * s + 4 * hf), e1 = *(const float4*)(sSC + 192 + 16 * s + 8 + 4 * hf);
;       vs[s].x = cvtpk(bflo(vnf[s].x) * e0.x, bfhi(vnf[s].x) * e0.y); vs[s].y = cvtpk(bflo(vnf[s].y) * e0.z, bfhi(vnf[s].y) * e0.w);
;       vs[s].z = cvtpk(bflo(vnf[s].z) * e1.x, bfhi(vnf[s].z) * e1.y); vs[s].w = cvtpk(bflo(vnf[s].w) * e1.z, bfhi(vnf[s].w) * e1.w);
;     }
;     {
;       u32x4 id1 = {0u, 0u, 0u, 0u}, id2 = {0u, 0u, 0u, 0u};
;       {
;         const int l15 = l31 & 15;
;         const int jsel = (((l15 >> 2) & 1) == hf) ? (4 * (l15 >> 3) + (l15 & 3)) : -1;
;         const int j1 = (l31 < 16) ? jsel : -1;
;         const int j2 = (l31 >= 16) ? jsel : -1;
;         const unsigned one_lo = 0x3f80u, one_hi = 0x3f800000u;
; #pragma unroll
;         for (int w = 0; w < 4; ++w) {
;           id1[w] = (j1 == 2 * w) ? one_lo : ((j1 == 2 * w + 1) ? one_hi : 0u);
;           id2[w] = (j2 == 2 * w) ? one_lo : ((j2 == 2 * w + 1) ? one_hi : 0u);
;         }
;       }
;       const bf16x8 B1 = __builtin_bit_cast(bf16x8, id1), B2 = __builtin_bit_cast(bf16x8, id2);
; #pragma unroll
;       for (int dt = 0; dt < 4; ++dt)
; #pragma unroll
;         for (int mt = 0; mt < 2; ++mt) {
;           f32x16 kt;
; #pragma unroll
;           for (int r = 0; r < 16; ++r) kt[r] = 0.f;
;           const u16* k0 = sk + (32 * mt + l31) * 136 + 32 * dt + 8 * hf;
;           kt = mfma32(*(const bf16x8*)(k0), B1, kt);
;           kt = mfma32(*(const bf16x8*)(k0 + 16), B2, kt);
; #pragma unroll
;           for (int s2 = 0; s2 < 2; ++s2) {
;             u32x4 af = {cvtpk(kt[8 * s2 + 0], kt[8 * s2 + 1]), cvtpk(kt[8 * s2 + 2], kt[8 * s2 + 3]), cvtpk(kt[8 * s2 + 4], kt[8 * s2 + 5]), cvtpk(kt[8 * s2 + 6], kt[8 * s2 + 7])};
;             S[dt] = mfma32(__builtin_bit_cast(bf16x8, af), __builtin_bit_cast(bf16x8, vs[2 * mt + s2]), S[dt]);
;           }
;         }
	v_pk_mul_f32 v[242:243], v[72:73], v[242:243]
	v_cvt_pk_bf16_f32 v84, v242, v243
	v_lshlrev_b32_e32 v244, 16, v113
	v_and_b32_e32 v245, 0xffff0000, v113
	v_pk_mul_f32 v[244:245], v[74:75], v[244:245]
	v_cvt_pk_bf16_f32 v85, v244, v245
	v_lshlrev_b32_e32 v242, 16, v114
	v_and_b32_e32 v243, 0xffff0000, v114
	s_waitcnt lgkmcnt(4)
	v_pk_mul_f32 v[242:243], v[76:77], v[242:243]
	v_cvt_pk_bf16_f32 v86, v242, v243
	v_lshlrev_b32_e32 v244, 16, v115
	v_and_b32_e32 v245, 0xffff0000, v115
	v_pk_mul_f32 v[244:245], v[78:79], v[244:245]
	v_cvt_pk_bf16_f32 v87, v244, v245
	ds_read_b128 v[64:67], v222 offset:54144
	ds_read_b128 v[68:71], v222 offset:54176
	ds_read_b128 v[72:75], v222 offset:54208
	ds_read_b128 v[76:79], v222 offset:54240
	v_cvt_pk_bf16_f32 v120, v120, v121
	v_cvt_pk_bf16_f32 v121, v122, v123
	v_cvt_pk_bf16_f32 v122, v124, v125
	v_cvt_pk_bf16_f32 v123, v126, v127
	s_nop 1
	v_mfma_f32_32x32x16_bf16 v[48:63], v[120:123], v[80:83], v[48:63]
	v_cvt_pk_bf16_f32 v124, v128, v129
	v_cvt_pk_bf16_f32 v125, v130, v131
	v_cvt_pk_bf16_f32 v126, v132, v133
	v_cvt_pk_bf16_f32 v127, v134, v135
	s_nop 1
	v_mfma_f32_32x32x16_bf16 v[48:63], v[124:127], v[84:87], v[48:63]
	s_waitcnt lgkmcnt(7)
	v_mfma_f32_32x32x16_bf16 v[120:135], v[226:229], v[96:99], 0
	s_waitcnt lgkmcnt(6)
	v_mfma_f32_32x32x16_bf16 v[120:135], v[230:233], v[100:103], v[120:135]
	v_lshlrev_b32_e32 v242, 16, v108
	v_and_b32_e32 v243, 0xffff0000, v108
	s_waitcnt lgkmcnt(3)
	v_pk_mul_f32 v[242:243], v[64:65], v[242:243]
	v_cvt_pk_bf16_f32 v88, v242, v243
	v_lshlrev_b32_e32 v244, 16, v109
	v_and_b32_e32 v245, 0xffff0000, v109
	v_pk_mul_f32 v[244:245], v[66:67], v[244:245]
	v_cvt_pk_bf16_f32 v89, v244, v245
	v_lshlrev_b32_e32 v242, 16, v110
	v_and_b32_e32 v243, 0xffff0000, v110
	s_waitcnt lgkmcnt(2)
	v_pk_mul_f32 v[242:243], v[68:69], v[242:243]
	v_cvt_pk_bf16_f32 v90, v242, v243
	v_lshlrev_b32_e32 v244, 16, v111
	v_and_b32_e32 v245, 0xffff0000, v111
	v_pk_mul_f32 v[244:245], v[70:71], v[244:245]
	v_cvt_pk_bf16_f32 v91, v244, v245
	v_lshlrev_b32_e32 v242, 16, v104
	v_and_b32_e32 v243, 0xffff0000, v104
	s_waitcnt lgkmcnt(1)
	v_pk_mul_f32 v[242:243], v[72:73], v[242:243]
	v_cvt_pk_bf16_f32 v104, v242, v243
	v_lshlrev_b32_e32 v244, 16, v105
	v_and_b32_e32 v245, 0xffff0000, v105
	v_pk_mul_f32 v[244:245], v[74:75], v[244:245]
	v_cvt_pk_bf16_f32 v105, v244, v245
	v_lshlrev_b32_e32 v242, 16, v106
	v_and_b32_e32 v243, 0xffff0000, v106
	s_waitcnt lgkmcnt(0)
	v_pk_mul_f32 v[242:243], v[76:77], v[242:243]
	v_cvt_pk_bf16_f32 v106, v242, v243
	v_lshlrev_b32_e32 v244, 16, v107
	v_and_b32_e32 v245, 0xffff0000, v107
	v_pk_mul_f32 v[244:245], v[78:79], v[244:245]
	v_cvt_pk_bf16_f32 v107, v244, v245
	v_pk_mul_f32 v[46:47], v[46:47], v[92:93] op_sel_hi:[1,0]
	v_pk_mul_f32 v[44:45], v[44:45], v[92:93] op_sel_hi:[1,0]
	v_pk_mul_f32 v[42:43], v[42:43], v[92:93] op_sel_hi:[1,0]
	v_pk_mul_f32 v[40:41], v[40:41], v[92:93] op_sel_hi:[1,0]
	v_pk_mul_f32 v[38:39], v[38:39], v[92:93] op_sel_hi:[1,0]
	v_pk_mul_f32 v[36:37], v[36:37], v[92:93] op_sel_hi:[1,0]
	v_pk_mul_f32 v[34:35], v[34:35], v[92:93] op_sel_hi:[1,0]
	v_pk_mul_f32 v[32:33], v[32:33], v[92:93] op_sel_hi:[1,0]
	v_cvt_pk_bf16_f32 v136, v136, v137
	v_cvt_pk_bf16_f32 v137, v138, v139
	v_cvt_pk_bf16_f32 v138, v140, v141
	v_cvt_pk_bf16_f32 v139, v142, v143
	s_nop 1
	v_mfma_f32_32x32x16_bf16 v[48:63], v[136:139], v[88:91], v[48:63]
	v_cvt_pk_bf16_f32 v140, v144, v145
	v_cvt_pk_bf16_f32 v141, v146, v147
	v_cvt_pk_bf16_f32 v142, v148, v149
	v_cvt_pk_bf16_f32 v143, v150, v151
	s_nop 1
	v_mfma_f32_32x32x16_bf16 v[48:63], v[140:143], v[104:107], v[48:63]
	v_mfma_f32_32x32x16_bf16 v[136:151], v[234:237], v[96:99], 0
	v_mfma_f32_32x32x16_bf16 v[136:151], v[238:241], v[100:103], v[136:151]
	ds_read_b128 v[226:229], v159 offset:128
	ds_read_b128 v[230:233], v159 offset:160
	ds_read_b128 v[234:237], v159 offset:8832
	ds_read_b128 v[238:241], v159 offset:8864
	v_pk_mul_f32 v[30:31], v[30:31], v[92:93] op_sel_hi:[1,0]
	v_pk_mul_f32 v[28:29], v[28:29], v[92:93] op_sel_hi:[1,0]
	v_pk_mul_f32 v[26:27], v[26:27], v[92:93] op_sel_hi:[1,0]
	v_pk_mul_f32 v[24:25], v[24:25], v[92:93] op_sel_hi:[1,0]
	v_pk_mul_f32 v[22:23], v[22:23], v[92:93] op_sel_hi:[1,0]
	v_pk_mul_f32 v[20:21], v[20:21], v[92:93] op_sel_hi:[1,0]
	v_pk_mul_f32 v[18:19], v[18:19], v[92:93] op_sel_hi:[1,0]
	v_pk_mul_f32 v[16:17], v[16:17], v[92:93] op_sel_hi:[1,0]
	v_cvt_pk_bf16_f32 v120, v120, v121
	v_cvt_pk_bf16_f32 v121, v122, v123
	v_cvt_pk_bf16_f32 v122, v124, v125
	v_cvt_pk_bf16_f32 v123, v126, v127
	s_nop 1
	v_mfma_f32_32x32x16_bf16 v[32:47], v[120:123], v[80:83], v[32:47]
	v_cvt_pk_bf16_f32 v124, v128, v129
	v_cvt_pk_bf16_f32 v125, v130, v131
	v_cvt_pk_bf16_f32 v126, v132, v133
	v_cvt_pk_bf16_f32 v127, v134, v135
	s_nop 1
	v_mfma_f32_32x32x16_bf16 v[32:47], v[124:127], v[84:87], v[32:47]
	s_waitcnt lgkmcnt(3)
; __device__ __forceinline__ unsigned cvtpk(float lo, float hi) { f32x2_t v = {lo, hi}; bf16x2_t b = __builtin_convertvector(v, bf16x2_t); return __builtin_bit_cast(unsigned, b); }
; __device__ __forceinline__ f32x16 mfma32(bf16x8 a, bf16x8 b, f32x16 c) { return __builtin_amdgcn_mfma_f32_32x32x16_bf16(a, b, c, 0, 0, 0); }
; __device__ __forceinline__ void lds_barrier() { asm volatile("s_waitcnt lgkmcnt(0)\n\ts_barrier" ::: "memory"); }
; __device__ __forceinline__ void scan_chunked(const Params& p, unsigned char* smem, int bh, f32x16 (&S)[4], const int c_begin, const int c_end) {
;     ...
; #pragma unroll
;       for (int dt = 0; dt < 4; ++dt)
; #pragma unroll
;         for (int mt = 0; mt < 2; ++mt) {
;           f32x16 kt;
; #pragma unroll
;           for (int r = 0; r < 16; ++r) kt[r] = 0.f;
;           const u16* k0 = sk + (32 * mt + l31) * 136 + 32 * dt + 8 * hf;
;           kt = mfma32(*(const bf16x8*)(k0), B1, kt);
;           kt = mfma32(*(const bf16x8*)(k0 + 16), B2, kt);
; #pragma unroll
;           for (int s2 = 0; s2 < 2; ++s2) {
;             u32x4 af = {cvtpk(kt[8 * s2 + 0], kt[8 * s2 + 1]), cvtpk(kt[8 * s2 + 2], kt[8 * s2 + 3]), cvtpk(kt[8 * s2 + 4], kt[8 * s2 + 5]), cvtpk(kt[8 * s2 + 6], kt[8 * s2 + 7])};
;             S[dt] = mfma32(__builtin_bit_cast(bf16x8, af), __builtin_bit_cast(bf16x8, vs[2 * mt + s2]), S[dt]);
;           }
;         }
;     }
;     lds_barrier();
	v_mfma_f32_32x32x16_bf16 v[120:135], v[226:229], v[96:99], 0
	s_waitcnt lgkmcnt(2)
	v_mfma_f32_32x32x16_bf16 v[120:135], v[230:233], v[100:103], v[120:135]
	v_pk_mul_f32 v[14:15], v[14:15], v[92:93] op_sel_hi:[1,0]
	v_pk_mul_f32 v[12:13], v[12:13], v[92:93] op_sel_hi:[1,0]
	v_pk_mul_f32 v[10:11], v[10:11], v[92:93] op_sel_hi:[1,0]
	v_pk_mul_f32 v[8:9], v[8:9], v[92:93] op_sel_hi:[1,0]
	v_pk_mul_f32 v[6:7], v[6:7], v[92:93] op_sel_hi:[1,0]
	v_pk_mul_f32 v[4:5], v[4:5], v[92:93] op_sel_hi:[1,0]
	v_pk_mul_f32 v[2:3], v[2:3], v[92:93] op_sel_hi:[1,0]
	v_pk_mul_f32 v[0:1], v[0:1], v[92:93] op_sel_hi:[1,0]
	v_cvt_pk_bf16_f32 v136, v136, v137
	v_cvt_pk_bf16_f32 v137, v138, v139
	v_cvt_pk_bf16_f32 v138, v140, v141
	v_cvt_pk_bf16_f32 v139, v142, v143
	s_nop 1
	v_mfma_f32_32x32x16_bf16 v[32:47], v[136:139], v[88:91], v[32:47]
	v_cvt_pk_bf16_f32 v140, v144, v145
	v_cvt_pk_bf16_f32 v141, v146, v147
	v_cvt_pk_bf16_f32 v142, v148, v149
	v_cvt_pk_bf16_f32 v143, v150, v151
	s_nop 1
	v_mfma_f32_32x32x16_bf16 v[32:47], v[140:143], v[104:107], v[32:47]
	s_waitcnt lgkmcnt(1)
	v_mfma_f32_32x32x16_bf16 v[136:151], v[234:237], v[96:99], 0
	s_waitcnt lgkmcnt(0)
	v_mfma_f32_32x32x16_bf16 v[136:151], v[238:241], v[100:103], v[136:151]
	ds_read_b128 v[226:229], v159 offset:192
	ds_read_b128 v[230:233], v159 offset:224
	ds_read_b128 v[234:237], v159 offset:8896
	ds_read_b128 v[238:241], v159 offset:8928
	v_cvt_pk_bf16_f32 v120, v120, v121
	v_cvt_pk_bf16_f32 v121, v122, v123
	v_cvt_pk_bf16_f32 v122, v124, v125
	v_cvt_pk_bf16_f32 v123, v126, v127
	s_nop 1
	v_mfma_f32_32x32x16_bf16 v[16:31], v[120:123], v[80:83], v[16:31]
	v_cvt_pk_bf16_f32 v124, v128, v129
	v_cvt_pk_bf16_f32 v125, v130, v131
	v_cvt_pk_bf16_f32 v126, v132, v133
	v_cvt_pk_bf16_f32 v127, v134, v135
	s_nop 1
	v_mfma_f32_32x32x16_bf16 v[16:31], v[124:127], v[84:87], v[16:31]
	s_waitcnt lgkmcnt(3)
	v_mfma_f32_32x32x16_bf16 v[120:135], v[226:229], v[96:99], 0
	s_waitcnt lgkmcnt(2)
	v_mfma_f32_32x32x16_bf16 v[120:135], v[230:233], v[100:103], v[120:135]
	v_cvt_pk_bf16_f32 v136, v136, v137
	v_cvt_pk_bf16_f32 v137, v138, v139
	v_cvt_pk_bf16_f32 v138, v140, v141
	v_cvt_pk_bf16_f32 v139, v142, v143
	s_nop 1
	v_mfma_f32_32x32x16_bf16 v[16:31], v[136:139], v[88:91], v[16:31]
	v_cvt_pk_bf16_f32 v140, v144, v145
	v_cvt_pk_bf16_f32 v141, v146, v147
	v_cvt_pk_bf16_f32 v142, v148, v149
	v_cvt_pk_bf16_f32 v143, v150, v151
	s_nop 1
	v_mfma_f32_32x32x16_bf16 v[16:31], v[140:143], v[104:107], v[16:31]
	s_waitcnt lgkmcnt(1)
	v_mfma_f32_32x32x16_bf16 v[136:151], v[234:237], v[96:99], 0
	s_waitcnt lgkmcnt(0)
	v_mfma_f32_32x32x16_bf16 v[136:151], v[238:241], v[100:103], v[136:151]
	s_waitcnt lgkmcnt(0)
	s_barrier
	v_cvt_pk_bf16_f32 v120, v120, v121
	v_cvt_pk_bf16_f32 v121, v122, v123
	v_cvt_pk_bf16_f32 v122, v124, v125
	v_cvt_pk_bf16_f32 v123, v126, v127
	s_nop 1
	v_mfma_f32_32x32x16_bf16 v[0:15], v[120:123], v[80:83], v[0:15]
	v_cvt_pk_bf16_f32 v124, v128, v129
	v_cvt_pk_bf16_f32 v125, v130, v131
	v_cvt_pk_bf16_f32 v126, v132, v133
	v_cvt_pk_bf16_f32 v127, v134, v135
	s_nop 1
	v_mfma_f32_32x32x16_bf16 v[0:15], v[124:127], v[84:87], v[0:15]
	v_cvt_pk_bf16_f32 v136, v136, v137
	v_cvt_pk_bf16_f32 v137, v138, v139
	v_cvt_pk_bf16_f32 v138, v140, v141
	v_cvt_pk_bf16_f32 v139, v142, v143
	s_nop 1
	v_mfma_f32_32x32x16_bf16 v[0:15], v[136:139], v[88:91], v[0:15]
	v_cvt_pk_bf16_f32 v140, v144, v145
	v_cvt_pk_bf16_f32 v141, v146, v147
	v_cvt_pk_bf16_f32 v142, v148, v149
	v_cvt_pk_bf16_f32 v143, v150, v151
	s_nop 1
	v_mfma_f32_32x32x16_bf16 v[0:15], v[140:143], v[104:107], v[0:15]
	s_add_i32 s7, s7, 1
	s_cmpk_eq_i32 s7, 0x81
	s_cbranch_scc1 .LBB0_320

; __device__ __forceinline__ void attn_item(const Params& p, unsigned char* smem, int b, int h, int qb, float lam) {
;     ...
;     float rsum = 0.f;
; #pragma unroll
;     for (int mt = 0; mt < 2; ++mt)
; #pragma unroll
;       for (int r = 0; r < 16; ++r) { float pv = __builtin_amdgcn_exp2f(st[mt][r] - m_new); st[mt][r] = pv; rsum += pv; }
;     l_run = l_run * alpha + rsum; m_run = m_new;
.LBB0_331:
	v_pk_add_f32 v[82:83], v[82:83], v[84:85]
	v_pk_add_f32 v[86:87], v[86:87], v[88:89]
	v_pk_add_f32 v[90:91], v[90:91], v[92:93]
	v_pk_add_f32 v[64:65], v[64:65], v[66:67]
	v_pk_add_f32 v[68:69], v[68:69], v[70:71]
	v_pk_add_f32 v[72:73], v[72:73], v[74:75]
	v_pk_add_f32 v[76:77], v[76:77], v[78:79]
	v_add_f32_e32 v81, v81, v217
	v_pk_add_f32 v[82:83], v[82:83], v[86:87]
	v_pk_add_f32 v[90:91], v[90:91], v[94:95]
	v_pk_add_f32 v[64:65], v[64:65], v[68:69]
	v_pk_add_f32 v[72:73], v[72:73], v[76:77]
	v_pk_add_f32 v[82:83], v[82:83], v[90:91]
	v_pk_add_f32 v[64:65], v[64:65], v[72:73]
	v_pk_add_f32 v[64:65], v[64:65], v[82:83]
	v_add_f32_e32 v64, v64, v65
	v_add_f32_e32 v64, v64, v81
	s_waitcnt lgkmcnt(0)
	s_barrier
	v_fma_f32 v217, v221, v80, v64
	s_addk_i32 s55, 0x80
	s_add_i32 s54, s54, 2
	s_cmp_lt_u32 s56, s19
	s_cbranch_scc0 .LBB0_323

; __device__ __forceinline__ void attn_item(const Params& p, unsigned char* smem, int b, int h, int qb, float lam) {
;     ...
;     float rsum = 0.f;
; #pragma unroll
;     for (int mt = 0; mt < 2; ++mt)
; #pragma unroll
;       for (int r = 0; r < 16; ++r) { float pv = __builtin_amdgcn_exp2f(st[mt][r] - m_new); st[mt][r] = pv; rsum += pv; }
;     l_run = l_run * alpha + rsum; m_run = m_new;
;     ...
;     if (kt + 1 < ntiles) {
;       if (kt + 3 < ntiles) gload(bk, bv, kt + 3);
.LBB0_338:
	v_pk_add_f32 v[82:83], v[82:83], v[84:85]
	v_pk_add_f32 v[86:87], v[86:87], v[88:89]
	v_pk_add_f32 v[90:91], v[90:91], v[92:93]
	v_pk_add_f32 v[64:65], v[64:65], v[66:67]
	v_pk_add_f32 v[68:69], v[68:69], v[70:71]
	v_pk_add_f32 v[72:73], v[72:73], v[74:75]
	v_pk_add_f32 v[76:77], v[76:77], v[78:79]
	v_add_f32_e32 v81, v81, v219
	v_pk_add_f32 v[82:83], v[82:83], v[86:87]
	v_pk_add_f32 v[90:91], v[90:91], v[94:95]
	v_pk_add_f32 v[64:65], v[64:65], v[68:69]
	v_pk_add_f32 v[72:73], v[72:73], v[76:77]
	v_pk_add_f32 v[82:83], v[82:83], v[90:91]
	v_pk_add_f32 v[64:65], v[64:65], v[72:73]
	v_pk_add_f32 v[64:65], v[64:65], v[82:83]
	v_add_f32_e32 v64, v64, v65
	v_add_f32_e32 v64, v64, v81
	s_waitcnt lgkmcnt(0)
	s_barrier
	v_fma_f32 v221, v217, v80, v64
	s_andn2_b64 vcc, exec, s[16:17]
	s_cbranch_vccnz .LBB0_345
	s_cmp_ge_u32 s54, s53
	s_cbranch_scc1 .LBB0_341
	v_add_u32_e32 v68, s55, v180
	v_add_u32_e32 v64, 0xc0, v68
	v_ashrrev_i32_e32 v65, 31, v64
	s_add_i32 s8, s55, 0xc0
	v_lshlrev_b64 v[64:65], 11, v[64:65]
	v_lshl_add_u64 v[64:65], v[192:193], 0, v[64:65]
	s_lshl_b64 s[16:17], s[8:9], 1
	v_lshl_add_u64 v[66:67], v[182:183], 0, s[16:17]
	global_load_dwordx4 v[148:151], v[64:65], off
	global_load_dwordx4 v[144:147], v[66:67], off
	v_add_u32_e32 v64, 0xd0, v68
	v_ashrrev_i32_e32 v65, 31, v64
	v_lshlrev_b64 v[64:65], 11, v[64:65]
	v_lshl_add_u64 v[64:65], v[192:193], 0, v[64:65]
	v_lshl_add_u64 v[66:67], v[184:185], 0, s[16:17]
	global_load_dwordx4 v[152:155], v[64:65], off
	global_load_dwordx4 v[156:159], v[66:67], off
	v_add_u32_e32 v64, 0xe0, v68
	v_ashrrev_i32_e32 v65, 31, v64
	v_lshlrev_b64 v[64:65], 11, v[64:65]
	v_lshl_add_u64 v[64:65], v[192:193], 0, v[64:65]
	v_lshl_add_u64 v[66:67], v[186:187], 0, s[16:17]
	global_load_dwordx4 v[164:167], v[64:65], off
	global_load_dwordx4 v[160:163], v[66:67], off
	v_add_u32_e32 v64, 0xf0, v68
	v_ashrrev_i32_e32 v65, 31, v64
	v_lshlrev_b64 v[64:65], 11, v[64:65]
	v_lshl_add_u64 v[64:65], v[192:193], 0, v[64:65]
	v_lshl_add_u64 v[66:67], v[190:191], 0, s[16:17]
	global_load_dwordx4 v[168:171], v[64:65], off
	global_load_dwordx4 v[172:175], v[66:67], off
